# final-norm sample rows: all 36 loads of a row in flight with scalar addressing (replaces the compiler's wait-per-load loop)
# speedup vs baseline: 1.0298x; 1.0001x over previous
; __device__ __forceinline__ float bf_lo(unsigned w) { return __uint_as_float(w << 16); }
; __device__ __forceinline__ float bf_hi(unsigned w) { return __uint_as_float(w & 0xffff0000u); }
; __device__ __forceinline__ void phase_final(const Args& a, int G, const int bid, const int tid) {
;     ...
;     for (int m = MP + gw; m < M; m += NGW) {
;         f32x4 v[4];
; #pragma unroll
;         for (int j = 0; j < 4; ++j) { const u32x2 w = ((const u32x2*)(XB + (size_t)m * DM))[lane + 64 * j]; v[j] = (f32x4){pg8::bf_lo(w.x), pg8::bf_hi(w.x), pg8::bf_lo(w.y), pg8::bf_hi(w.y)}; }
;         float ss = 0.f; const float r2s = __builtin_amdgcn_rcpf(rs3[m] * (1.0f / DM) + EPS);
; #pragma unroll
;         for (int j = 0; j < 4; ++j) {
;             f32x4 p = {0.f, 0.f, 0.f, 0.f};
; #pragma unroll
;             for (int z = 0; z < 8; ++z) { const u32x2 sw = ((const u32x2*)(SL + ((size_t)z * MS + (m - MP)) * DM))[lane + 64 * j]; p += (f32x4){pg8::bf_lo(sw.x), pg8::bf_hi(sw.x), pg8::bf_lo(sw.y), pg8::bf_hi(sw.y)}; }
;             v[j] += p * r2s;
;             ss += (v[j].x * v[j].x + v[j].y * v[j].y) + (v[j].z * v[j].z + v[j].w * v[j].w); }
.LBB0_16:
.Lfin_row:
	v_readfirstlane_b32 s16, v20
	v_and_b32_e32 v34, 63, v162
	v_lshlrev_b32_e32 v16, 3, v34
	v_lshlrev_b32_e32 v17, 4, v34
	s_nop 0
	s_add_u32 s17, s16, 0x10000
	s_lshl_b32 s18, s17, 11
	s_add_u32 s8, s26, s18
	s_addc_u32 s9, s27, 0
	s_add_u32 s8, s8, 0x4800000
	s_addc_u32 s9, s9, 0
	s_lshl_b32 s18, s17, 2
	s_add_u32 s14, s26, s18
	s_addc_u32 s15, s27, 0
	s_load_dword s18, s[14:15], 0xc6000
	s_lshl_b32 s19, s16, 11
	s_add_u32 s10, s26, s19
	s_addc_u32 s11, s27, 0
	s_add_u32 s10, s10, 0x2dc00000
	s_addc_u32 s11, s11, 0
	global_load_dwordx2 v[26:27], v16, s[8:9] offset:0
	global_load_dwordx2 v[28:29], v16, s[8:9] offset:512
	global_load_dwordx2 v[30:31], v16, s[8:9] offset:1024
	global_load_dwordx2 v[32:33], v16, s[8:9] offset:1536
	global_load_dwordx2 v[64:65], v16, s[10:11] offset:0
	global_load_dwordx2 v[66:67], v16, s[10:11] offset:512
	global_load_dwordx2 v[68:69], v16, s[10:11] offset:1024
	global_load_dwordx2 v[70:71], v16, s[10:11] offset:1536
	s_add_u32 s10, s10, 0x400000
	s_addc_u32 s11, s11, 0
	global_load_dwordx2 v[72:73], v16, s[10:11] offset:0
	global_load_dwordx2 v[74:75], v16, s[10:11] offset:512
	global_load_dwordx2 v[76:77], v16, s[10:11] offset:1024
	global_load_dwordx2 v[78:79], v16, s[10:11] offset:1536
	s_add_u32 s10, s10, 0x400000
	s_addc_u32 s11, s11, 0
	global_load_dwordx2 v[80:81], v16, s[10:11] offset:0
	global_load_dwordx2 v[82:83], v16, s[10:11] offset:512
	global_load_dwordx2 v[84:85], v16, s[10:11] offset:1024
	global_load_dwordx2 v[86:87], v16, s[10:11] offset:1536
	s_add_u32 s10, s10, 0x400000
	s_addc_u32 s11, s11, 0
	global_load_dwordx2 v[88:89], v16, s[10:11] offset:0
	global_load_dwordx2 v[90:91], v16, s[10:11] offset:512
	global_load_dwordx2 v[92:93], v16, s[10:11] offset:1024
	global_load_dwordx2 v[94:95], v16, s[10:11] offset:1536
	s_add_u32 s10, s10, 0x400000
	s_addc_u32 s11, s11, 0
	global_load_dwordx2 v[96:97], v16, s[10:11] offset:0
	global_load_dwordx2 v[98:99], v16, s[10:11] offset:512
	global_load_dwordx2 v[100:101], v16, s[10:11] offset:1024
	global_load_dwordx2 v[102:103], v16, s[10:11] offset:1536
	s_add_u32 s10, s10, 0x400000
	s_addc_u32 s11, s11, 0
	global_load_dwordx2 v[104:105], v16, s[10:11] offset:0
	global_load_dwordx2 v[106:107], v16, s[10:11] offset:512
	global_load_dwordx2 v[108:109], v16, s[10:11] offset:1024
	global_load_dwordx2 v[110:111], v16, s[10:11] offset:1536
	s_add_u32 s10, s10, 0x400000
	s_addc_u32 s11, s11, 0
	global_load_dwordx2 v[112:113], v16, s[10:11] offset:0
	global_load_dwordx2 v[114:115], v16, s[10:11] offset:512
	global_load_dwordx2 v[116:117], v16, s[10:11] offset:1024
	global_load_dwordx2 v[118:119], v16, s[10:11] offset:1536
	s_add_u32 s10, s10, 0x400000
	s_addc_u32 s11, s11, 0
	global_load_dwordx2 v[120:121], v16, s[10:11] offset:0
	global_load_dwordx2 v[122:123], v16, s[10:11] offset:512
	global_load_dwordx2 v[124:125], v16, s[10:11] offset:1024
	global_load_dwordx2 v[126:127], v16, s[10:11] offset:1536
	s_waitcnt lgkmcnt(0)
	v_mov_b32_e32 v22, s18
	v_fmamk_f32 v22, v22, 0x3a800000, v197
	v_rcp_f32_e32 v22, v22
	v_mov_b32_e32 v23, 0
	s_waitcnt vmcnt(0)
	v_mov_b32_e32 v60, 0
	v_mov_b32_e32 v61, 0
	v_mov_b32_e32 v62, 0
	v_mov_b32_e32 v63, 0
	v_lshlrev_b32_e32 v34, 16, v64
	v_and_b32_e32 v52, 0xffff0000, v64
	v_lshlrev_b32_e32 v53, 16, v65
	v_and_b32_e32 v59, 0xffff0000, v65
	v_add_f32_e32 v60, v60, v34
	v_add_f32_e32 v61, v61, v52
	v_add_f32_e32 v62, v62, v53
	v_add_f32_e32 v63, v63, v59
	v_lshlrev_b32_e32 v34, 16, v72
	v_and_b32_e32 v52, 0xffff0000, v72
	v_lshlrev_b32_e32 v53, 16, v73
	v_and_b32_e32 v59, 0xffff0000, v73
	v_add_f32_e32 v60, v60, v34
	v_add_f32_e32 v61, v61, v52
	v_add_f32_e32 v62, v62, v53
	v_add_f32_e32 v63, v63, v59
	v_lshlrev_b32_e32 v34, 16, v80
	v_and_b32_e32 v52, 0xffff0000, v80
	v_lshlrev_b32_e32 v53, 16, v81
	v_and_b32_e32 v59, 0xffff0000, v81
	v_add_f32_e32 v60, v60, v34
	v_add_f32_e32 v61, v61, v52
	v_add_f32_e32 v62, v62, v53
	v_add_f32_e32 v63, v63, v59
	v_lshlrev_b32_e32 v34, 16, v88
	v_and_b32_e32 v52, 0xffff0000, v88
	v_lshlrev_b32_e32 v53, 16, v89
	v_and_b32_e32 v59, 0xffff0000, v89
	v_add_f32_e32 v60, v60, v34
	v_add_f32_e32 v61, v61, v52
	v_add_f32_e32 v62, v62, v53
	v_add_f32_e32 v63, v63, v59
	v_lshlrev_b32_e32 v34, 16, v96
	v_and_b32_e32 v52, 0xffff0000, v96
	v_lshlrev_b32_e32 v53, 16, v97
	v_and_b32_e32 v59, 0xffff0000, v97
	v_add_f32_e32 v60, v60, v34
	v_add_f32_e32 v61, v61, v52
	v_add_f32_e32 v62, v62, v53
	v_add_f32_e32 v63, v63, v59
	v_lshlrev_b32_e32 v34, 16, v104
	v_and_b32_e32 v52, 0xffff0000, v104
	v_lshlrev_b32_e32 v53, 16, v105
	v_and_b32_e32 v59, 0xffff0000, v105
	v_add_f32_e32 v60, v60, v34
	v_add_f32_e32 v61, v61, v52
	v_add_f32_e32 v62, v62, v53
	v_add_f32_e32 v63, v63, v59
	v_lshlrev_b32_e32 v34, 16, v112
	v_and_b32_e32 v52, 0xffff0000, v112
	v_lshlrev_b32_e32 v53, 16, v113
	v_and_b32_e32 v59, 0xffff0000, v113
	v_add_f32_e32 v60, v60, v34
	v_add_f32_e32 v61, v61, v52
	v_add_f32_e32 v62, v62, v53
	v_add_f32_e32 v63, v63, v59
	v_lshlrev_b32_e32 v34, 16, v120
	v_and_b32_e32 v52, 0xffff0000, v120
	v_lshlrev_b32_e32 v53, 16, v121
	v_and_b32_e32 v59, 0xffff0000, v121
	v_add_f32_e32 v60, v60, v34
	v_add_f32_e32 v61, v61, v52
	v_add_f32_e32 v62, v62, v53
	v_add_f32_e32 v63, v63, v59
	v_lshlrev_b32_e32 v34, 16, v26
	v_and_b32_e32 v52, 0xffff0000, v26
	v_lshlrev_b32_e32 v53, 16, v27
	v_and_b32_e32 v59, 0xffff0000, v27
	v_fma_f32 v36, v60, v22, v34
	v_fma_f32 v37, v61, v22, v52
	v_fma_f32 v38, v62, v22, v53
	v_fma_f32 v39, v63, v22, v59
	v_mul_f32_e32 v34, v36, v36
	v_fma_f32 v34, v37, v37, v34
	v_mul_f32_e32 v52, v38, v38
	v_fma_f32 v52, v39, v39, v52
	v_add_f32_e32 v34, v34, v52
; __device__ __forceinline__ float bf_lo(unsigned w) { return __uint_as_float(w << 16); }
; __device__ __forceinline__ float bf_hi(unsigned w) { return __uint_as_float(w & 0xffff0000u); }
; __device__ __forceinline__ void phase_final(const Args& a, int G, const int bid, const int tid) {
;     ...
;         for (int j = 0; j < 4; ++j) {
;             f32x4 p = {0.f, 0.f, 0.f, 0.f};
; #pragma unroll
;             for (int z = 0; z < 8; ++z) { const u32x2 sw = ((const u32x2*)(SL + ((size_t)z * MS + (m - MP)) * DM))[lane + 64 * j]; p += (f32x4){pg8::bf_lo(sw.x), pg8::bf_hi(sw.x), pg8::bf_lo(sw.y), pg8::bf_hi(sw.y)}; }
;             v[j] += p * r2s;
;             ss += (v[j].x * v[j].x + v[j].y * v[j].y) + (v[j].z * v[j].z + v[j].w * v[j].w); }
	v_add_f32_e32 v23, v23, v34
	v_mov_b32_e32 v60, 0
	v_mov_b32_e32 v61, 0
	v_mov_b32_e32 v62, 0
	v_mov_b32_e32 v63, 0
	v_lshlrev_b32_e32 v34, 16, v66
	v_and_b32_e32 v52, 0xffff0000, v66
	v_lshlrev_b32_e32 v53, 16, v67
	v_and_b32_e32 v59, 0xffff0000, v67
	v_add_f32_e32 v60, v60, v34
	v_add_f32_e32 v61, v61, v52
	v_add_f32_e32 v62, v62, v53
	v_add_f32_e32 v63, v63, v59
	v_lshlrev_b32_e32 v34, 16, v74
	v_and_b32_e32 v52, 0xffff0000, v74
	v_lshlrev_b32_e32 v53, 16, v75
	v_and_b32_e32 v59, 0xffff0000, v75
	v_add_f32_e32 v60, v60, v34
	v_add_f32_e32 v61, v61, v52
	v_add_f32_e32 v62, v62, v53
	v_add_f32_e32 v63, v63, v59
	v_lshlrev_b32_e32 v34, 16, v82
	v_and_b32_e32 v52, 0xffff0000, v82
	v_lshlrev_b32_e32 v53, 16, v83
	v_and_b32_e32 v59, 0xffff0000, v83
	v_add_f32_e32 v60, v60, v34
	v_add_f32_e32 v61, v61, v52
	v_add_f32_e32 v62, v62, v53
	v_add_f32_e32 v63, v63, v59
	v_lshlrev_b32_e32 v34, 16, v90
	v_and_b32_e32 v52, 0xffff0000, v90
	v_lshlrev_b32_e32 v53, 16, v91
	v_and_b32_e32 v59, 0xffff0000, v91
	v_add_f32_e32 v60, v60, v34
	v_add_f32_e32 v61, v61, v52
	v_add_f32_e32 v62, v62, v53
	v_add_f32_e32 v63, v63, v59
	v_lshlrev_b32_e32 v34, 16, v98
	v_and_b32_e32 v52, 0xffff0000, v98
	v_lshlrev_b32_e32 v53, 16, v99
	v_and_b32_e32 v59, 0xffff0000, v99
	v_add_f32_e32 v60, v60, v34
	v_add_f32_e32 v61, v61, v52
	v_add_f32_e32 v62, v62, v53
	v_add_f32_e32 v63, v63, v59
	v_lshlrev_b32_e32 v34, 16, v106
	v_and_b32_e32 v52, 0xffff0000, v106
	v_lshlrev_b32_e32 v53, 16, v107
	v_and_b32_e32 v59, 0xffff0000, v107
	v_add_f32_e32 v60, v60, v34
	v_add_f32_e32 v61, v61, v52
	v_add_f32_e32 v62, v62, v53
	v_add_f32_e32 v63, v63, v59
	v_lshlrev_b32_e32 v34, 16, v114
	v_and_b32_e32 v52, 0xffff0000, v114
	v_lshlrev_b32_e32 v53, 16, v115
	v_and_b32_e32 v59, 0xffff0000, v115
	v_add_f32_e32 v60, v60, v34
	v_add_f32_e32 v61, v61, v52
	v_add_f32_e32 v62, v62, v53
	v_add_f32_e32 v63, v63, v59
	v_lshlrev_b32_e32 v34, 16, v122
	v_and_b32_e32 v52, 0xffff0000, v122
	v_lshlrev_b32_e32 v53, 16, v123
	v_and_b32_e32 v59, 0xffff0000, v123
	v_add_f32_e32 v60, v60, v34
	v_add_f32_e32 v61, v61, v52
	v_add_f32_e32 v62, v62, v53
	v_add_f32_e32 v63, v63, v59
	v_lshlrev_b32_e32 v34, 16, v28
	v_and_b32_e32 v52, 0xffff0000, v28
	v_lshlrev_b32_e32 v53, 16, v29
	v_and_b32_e32 v59, 0xffff0000, v29
	v_fma_f32 v40, v60, v22, v34
	v_fma_f32 v41, v61, v22, v52
	v_fma_f32 v42, v62, v22, v53
	v_fma_f32 v43, v63, v22, v59
	v_mul_f32_e32 v34, v40, v40
	v_fma_f32 v34, v41, v41, v34
	v_mul_f32_e32 v52, v42, v42
	v_fma_f32 v52, v43, v43, v52
	v_add_f32_e32 v34, v34, v52
	v_add_f32_e32 v23, v23, v34
	v_mov_b32_e32 v60, 0
	v_mov_b32_e32 v61, 0
	v_mov_b32_e32 v62, 0
	v_mov_b32_e32 v63, 0
	v_lshlrev_b32_e32 v34, 16, v68
	v_and_b32_e32 v52, 0xffff0000, v68
	v_lshlrev_b32_e32 v53, 16, v69
	v_and_b32_e32 v59, 0xffff0000, v69
	v_add_f32_e32 v60, v60, v34
	v_add_f32_e32 v61, v61, v52
	v_add_f32_e32 v62, v62, v53
	v_add_f32_e32 v63, v63, v59
	v_lshlrev_b32_e32 v34, 16, v76
	v_and_b32_e32 v52, 0xffff0000, v76
	v_lshlrev_b32_e32 v53, 16, v77
	v_and_b32_e32 v59, 0xffff0000, v77
	v_add_f32_e32 v60, v60, v34
	v_add_f32_e32 v61, v61, v52
	v_add_f32_e32 v62, v62, v53
	v_add_f32_e32 v63, v63, v59
	v_lshlrev_b32_e32 v34, 16, v84
	v_and_b32_e32 v52, 0xffff0000, v84
	v_lshlrev_b32_e32 v53, 16, v85
	v_and_b32_e32 v59, 0xffff0000, v85
	v_add_f32_e32 v60, v60, v34
	v_add_f32_e32 v61, v61, v52
	v_add_f32_e32 v62, v62, v53
	v_add_f32_e32 v63, v63, v59
	v_lshlrev_b32_e32 v34, 16, v92
	v_and_b32_e32 v52, 0xffff0000, v92
	v_lshlrev_b32_e32 v53, 16, v93
	v_and_b32_e32 v59, 0xffff0000, v93
	v_add_f32_e32 v60, v60, v34
	v_add_f32_e32 v61, v61, v52
	v_add_f32_e32 v62, v62, v53
	v_add_f32_e32 v63, v63, v59
	v_lshlrev_b32_e32 v34, 16, v100
	v_and_b32_e32 v52, 0xffff0000, v100
	v_lshlrev_b32_e32 v53, 16, v101
	v_and_b32_e32 v59, 0xffff0000, v101
	v_add_f32_e32 v60, v60, v34
	v_add_f32_e32 v61, v61, v52
	v_add_f32_e32 v62, v62, v53
	v_add_f32_e32 v63, v63, v59
	v_lshlrev_b32_e32 v34, 16, v108
	v_and_b32_e32 v52, 0xffff0000, v108
	v_lshlrev_b32_e32 v53, 16, v109
	v_and_b32_e32 v59, 0xffff0000, v109
	v_add_f32_e32 v60, v60, v34
	v_add_f32_e32 v61, v61, v52
	v_add_f32_e32 v62, v62, v53
	v_add_f32_e32 v63, v63, v59
	v_lshlrev_b32_e32 v34, 16, v116
	v_and_b32_e32 v52, 0xffff0000, v116
	v_lshlrev_b32_e32 v53, 16, v117
	v_and_b32_e32 v59, 0xffff0000, v117
	v_add_f32_e32 v60, v60, v34
	v_add_f32_e32 v61, v61, v52
	v_add_f32_e32 v62, v62, v53
	v_add_f32_e32 v63, v63, v59
	v_lshlrev_b32_e32 v34, 16, v124
	v_and_b32_e32 v52, 0xffff0000, v124
	v_lshlrev_b32_e32 v53, 16, v125
	v_and_b32_e32 v59, 0xffff0000, v125
	v_add_f32_e32 v60, v60, v34
	v_add_f32_e32 v61, v61, v52
	v_add_f32_e32 v62, v62, v53
	v_add_f32_e32 v63, v63, v59
	v_lshlrev_b32_e32 v34, 16, v30
	v_and_b32_e32 v52, 0xffff0000, v30
; __device__ __forceinline__ float bf_lo(unsigned w) { return __uint_as_float(w << 16); }
; __device__ __forceinline__ float bf_hi(unsigned w) { return __uint_as_float(w & 0xffff0000u); }
; __device__ __forceinline__ void phase_final(const Args& a, int G, const int bid, const int tid) {
;     ...
;         for (int j = 0; j < 4; ++j) {
;             f32x4 p = {0.f, 0.f, 0.f, 0.f};
; #pragma unroll
;             for (int z = 0; z < 8; ++z) { const u32x2 sw = ((const u32x2*)(SL + ((size_t)z * MS + (m - MP)) * DM))[lane + 64 * j]; p += (f32x4){pg8::bf_lo(sw.x), pg8::bf_hi(sw.x), pg8::bf_lo(sw.y), pg8::bf_hi(sw.y)}; }
;             v[j] += p * r2s;
;             ss += (v[j].x * v[j].x + v[j].y * v[j].y) + (v[j].z * v[j].z + v[j].w * v[j].w); }
;         const float r = __builtin_amdgcn_rsqf(wave_sum(ss) * (1.0f / DM) + EPS);
;         f32x4* yr = (f32x4*)(a.out + O_Y + (size_t)m * DM);
; #pragma unroll
;         for (int j = 0; j < 4; ++j) __builtin_nontemporal_store(v[j] * r * gv[j], yr + lane + 64 * j);
;     }
	v_lshlrev_b32_e32 v53, 16, v31
	v_and_b32_e32 v59, 0xffff0000, v31
	v_fma_f32 v44, v60, v22, v34
	v_fma_f32 v45, v61, v22, v52
	v_fma_f32 v46, v62, v22, v53
	v_fma_f32 v47, v63, v22, v59
	v_mul_f32_e32 v34, v44, v44
	v_fma_f32 v34, v45, v45, v34
	v_mul_f32_e32 v52, v46, v46
	v_fma_f32 v52, v47, v47, v52
	v_add_f32_e32 v34, v34, v52
	v_add_f32_e32 v23, v23, v34
	v_mov_b32_e32 v60, 0
	v_mov_b32_e32 v61, 0
	v_mov_b32_e32 v62, 0
	v_mov_b32_e32 v63, 0
	v_lshlrev_b32_e32 v34, 16, v70
	v_and_b32_e32 v52, 0xffff0000, v70
	v_lshlrev_b32_e32 v53, 16, v71
	v_and_b32_e32 v59, 0xffff0000, v71
	v_add_f32_e32 v60, v60, v34
	v_add_f32_e32 v61, v61, v52
	v_add_f32_e32 v62, v62, v53
	v_add_f32_e32 v63, v63, v59
	v_lshlrev_b32_e32 v34, 16, v78
	v_and_b32_e32 v52, 0xffff0000, v78
	v_lshlrev_b32_e32 v53, 16, v79
	v_and_b32_e32 v59, 0xffff0000, v79
	v_add_f32_e32 v60, v60, v34
	v_add_f32_e32 v61, v61, v52
	v_add_f32_e32 v62, v62, v53
	v_add_f32_e32 v63, v63, v59
	v_lshlrev_b32_e32 v34, 16, v86
	v_and_b32_e32 v52, 0xffff0000, v86
	v_lshlrev_b32_e32 v53, 16, v87
	v_and_b32_e32 v59, 0xffff0000, v87
	v_add_f32_e32 v60, v60, v34
	v_add_f32_e32 v61, v61, v52
	v_add_f32_e32 v62, v62, v53
	v_add_f32_e32 v63, v63, v59
	v_lshlrev_b32_e32 v34, 16, v94
	v_and_b32_e32 v52, 0xffff0000, v94
	v_lshlrev_b32_e32 v53, 16, v95
	v_and_b32_e32 v59, 0xffff0000, v95
	v_add_f32_e32 v60, v60, v34
	v_add_f32_e32 v61, v61, v52
	v_add_f32_e32 v62, v62, v53
	v_add_f32_e32 v63, v63, v59
	v_lshlrev_b32_e32 v34, 16, v102
	v_and_b32_e32 v52, 0xffff0000, v102
	v_lshlrev_b32_e32 v53, 16, v103
	v_and_b32_e32 v59, 0xffff0000, v103
	v_add_f32_e32 v60, v60, v34
	v_add_f32_e32 v61, v61, v52
	v_add_f32_e32 v62, v62, v53
	v_add_f32_e32 v63, v63, v59
	v_lshlrev_b32_e32 v34, 16, v110
	v_and_b32_e32 v52, 0xffff0000, v110
	v_lshlrev_b32_e32 v53, 16, v111
	v_and_b32_e32 v59, 0xffff0000, v111
	v_add_f32_e32 v60, v60, v34
	v_add_f32_e32 v61, v61, v52
	v_add_f32_e32 v62, v62, v53
	v_add_f32_e32 v63, v63, v59
	v_lshlrev_b32_e32 v34, 16, v118
	v_and_b32_e32 v52, 0xffff0000, v118
	v_lshlrev_b32_e32 v53, 16, v119
	v_and_b32_e32 v59, 0xffff0000, v119
	v_add_f32_e32 v60, v60, v34
	v_add_f32_e32 v61, v61, v52
	v_add_f32_e32 v62, v62, v53
	v_add_f32_e32 v63, v63, v59
	v_lshlrev_b32_e32 v34, 16, v126
	v_and_b32_e32 v52, 0xffff0000, v126
	v_lshlrev_b32_e32 v53, 16, v127
	v_and_b32_e32 v59, 0xffff0000, v127
	v_add_f32_e32 v60, v60, v34
	v_add_f32_e32 v61, v61, v52
	v_add_f32_e32 v62, v62, v53
	v_add_f32_e32 v63, v63, v59
	v_lshlrev_b32_e32 v34, 16, v32
	v_and_b32_e32 v52, 0xffff0000, v32
	v_lshlrev_b32_e32 v53, 16, v33
	v_and_b32_e32 v59, 0xffff0000, v33
	v_fma_f32 v48, v60, v22, v34
	v_fma_f32 v49, v61, v22, v52
	v_fma_f32 v50, v62, v22, v53
	v_fma_f32 v51, v63, v22, v59
	v_mul_f32_e32 v34, v48, v48
	v_fma_f32 v34, v49, v49, v34
	v_mul_f32_e32 v52, v50, v50
	v_fma_f32 v52, v51, v51, v52
	v_add_f32_e32 v34, v34, v52
	v_add_f32_e32 v23, v23, v34
	ds_bpermute_b32 v34, v35, v23
	s_waitcnt lgkmcnt(0)
	v_add_f32_e32 v23, v23, v34
	ds_bpermute_b32 v34, v54, v23
	s_waitcnt lgkmcnt(0)
	v_add_f32_e32 v23, v23, v34
	ds_bpermute_b32 v34, v55, v23
	s_waitcnt lgkmcnt(0)
	v_add_f32_e32 v23, v23, v34
	ds_bpermute_b32 v34, v56, v23
	s_waitcnt lgkmcnt(0)
	v_add_f32_e32 v23, v23, v34
	ds_bpermute_b32 v34, v57, v23
	s_waitcnt lgkmcnt(0)
	v_add_f32_e32 v23, v23, v34
	ds_bpermute_b32 v34, v58, v23
	s_waitcnt lgkmcnt(0)
	v_add_f32_e32 v23, v23, v34
	v_fmamk_f32 v23, v23, 0x3a800000, v197
	v_rsq_f32_e32 v23, v23
	v_readlane_b32 s12, v253, 44
	v_readlane_b32 s13, v253, 45
	s_lshl_b32 s18, s17, 12
	s_nop 1
	s_add_u32 s12, s12, s18
	s_addc_u32 s13, s13, 0
	v_mul_f32_e32 v64, v36, v23
	v_mul_f32_e32 v64, v0, v64
	v_mul_f32_e32 v65, v37, v23
	v_mul_f32_e32 v65, v1, v65
	v_mul_f32_e32 v66, v38, v23
	v_mul_f32_e32 v66, v2, v66
	v_mul_f32_e32 v67, v39, v23
	v_mul_f32_e32 v67, v3, v67
	global_store_dwordx4 v17, v[64:67], s[12:13] offset:0 nt
	v_mul_f32_e32 v68, v40, v23
	v_mul_f32_e32 v68, v4, v68
	v_mul_f32_e32 v69, v41, v23
	v_mul_f32_e32 v69, v5, v69
	v_mul_f32_e32 v70, v42, v23
	v_mul_f32_e32 v70, v6, v70
	v_mul_f32_e32 v71, v43, v23
	v_mul_f32_e32 v71, v7, v71
	global_store_dwordx4 v17, v[68:71], s[12:13] offset:1024 nt
	v_mul_f32_e32 v72, v44, v23
	v_mul_f32_e32 v72, v8, v72
	v_mul_f32_e32 v73, v45, v23
	v_mul_f32_e32 v73, v9, v73
	v_mul_f32_e32 v74, v46, v23
	v_mul_f32_e32 v74, v10, v74
	v_mul_f32_e32 v75, v47, v23
	v_mul_f32_e32 v75, v11, v75
	global_store_dwordx4 v17, v[72:75], s[12:13] offset:2048 nt
	v_mul_f32_e32 v76, v48, v23
	v_mul_f32_e32 v76, v12, v76
	v_mul_f32_e32 v77, v49, v23
	v_mul_f32_e32 v77, v13, v77
	v_mul_f32_e32 v78, v50, v23
	v_mul_f32_e32 v78, v14, v78
	v_mul_f32_e32 v79, v51, v23
	v_mul_f32_e32 v79, v15, v79
	global_store_dwordx4 v17, v[76:79], s[12:13] offset:3072 nt
	s_branch .LBB0_17
